# residual-update epilogue in the down GEMM (layers 1-2), two column passes with six row groups in flight; norm1 of layers 2-3 reads XB only
# speedup vs baseline: 1.0005x; 1.0005x over previous
; #define LAS __attribute__((address_space(3)))
; __device__ __forceinline__ unsigned cvt_pk_bf16(float lo, float hi) { const f32x2 v = {lo, hi}; return __builtin_bit_cast(unsigned, __builtin_convertvector(v, bf16x2_t)); }
; __device__ __forceinline__ float bf_lo(unsigned u) { return __uint_as_float(u << 16); }
; __device__ __forceinline__ float bf_hi(unsigned u) { return __uint_as_float(u & 0xffff0000u); }
;     template <class Sched> __device__ __forceinline__ void operator()(const f32x4 (&acc)[2][2][4][2], const Unit& u, const Sched& S, int wr, int wc, int fr, int fq) const {
;     ...
;                 for (int m = 0; m < 4; ++m) { bf16_t* rowp = base + (size_t)(rl0 + ai * HALF + m * 16) * ldo + cl0;
; #pragma unroll
;                     for (int bj = 0; bj < 2; ++bj) { const f32x4 v0 = acc[ai][bj][m][0], v1 = acc[ai][bj][m][1];
;                         u32x4 w; w.x = cvt_pk_bf16(v0[0], v0[1]); w.y = cvt_pk_bf16(v0[2], v0[3]); w.z = cvt_pk_bf16(v1[0], v1[1]); w.w = cvt_pk_bf16(v1[2], v1[3]);
;                         *(u32x4*)(rowp + bj * HALF) = w; } }
; __device__ __forceinline__ void norm_mod_phase(Frame& F, int L, const float* gvec, int sh_chunk, int nrows, const float* pg, const float* pg2, const float* xlat, const float* xctx) {
;     ...
;         if (h2) {
;             const LAS f32x4* gq = vq + 3 * (D / 4); u32x2* xw_ = (u32x2*)((bf16_t*)(F.ws + WS_XB) + (size_t)r * D) + lane;
; #pragma unroll
;             for (int j = 0; j < 8; ++j) { const u32x2 yy = aux[1][j]; const f32x4 y4 = {bf_lo(yy.x), bf_hi(yy.x), bf_lo(yy.y), bf_hi(yy.y)}; v[j] += gq[64 * j] * y4; u32x2 w; w.x = cvt_pk_bf16(v[j].x, v[j].y); w.y = cvt_pk_bf16(v[j].z, v[j].w); xw_[64 * j] = w; }
;         }
.Ldown_res_epi:
	s_lshl_b32 s4, s30, 20
	s_lshl_b32 s5, s34, 9
	s_add_u32 s4, s4, s5
	s_add_u32 s4, s4, 0x4f300000
	s_add_u32 s4, s66, s4
	s_addc_u32 s5, s67, 0
	s_lshr_b32 s17, s30, 3
	s_mul_i32 s27, s82, 9
	s_add_i32 s17, s17, s27
	s_mul_i32 s17, s17, 0xc000
	s_lshl_b32 s27, s34, 10
	s_add_i32 s17, s17, s27
	s_add_i32 s17, s17, 0x104000
	s_add_u32 s30, s66, s17
	s_addc_u32 s31, s67, 0
	s_add_u32 s34, s30, 0x6000
	s_addc_u32 s35, s31, 0
	v_lshl_add_u64 v[156:157], v[136:137], 1, s[4:5]
	s_mov_b32 s100, 0xf7000000
	s_mov_b32 s101, -1
	s_movk_i32 s17, 0x800
	v_lshl_add_u64 v[158:159], v[136:137], 2, s[30:31]
	global_load_dwordx4 v[178:181], v[158:159], off
	global_load_dwordx4 v[182:185], v[158:159], off offset:16
	v_lshl_add_u64 v[246:247], v[136:137], 2, s[34:35]
	global_load_dwordx4 v[186:189], v[246:247], off
	global_load_dwordx4 v[190:193], v[246:247], off offset:16
	v_mad_i64_i32 v[158:159], vcc, s17, v134, 0
	v_lshl_add_u64 v[158:159], v[158:159], 1, v[156:157]
	v_lshl_add_u64 v[246:247], v[158:159], 0, s[100:101]
	global_load_dwordx4 v[194:197], v[158:159], off
	global_load_dwordx4 v[198:201], v[246:247], off
	v_mad_i64_i32 v[158:159], vcc, s17, v138, 0
	v_lshl_add_u64 v[158:159], v[158:159], 1, v[156:157]
	v_lshl_add_u64 v[246:247], v[158:159], 0, s[100:101]
	global_load_dwordx4 v[202:205], v[158:159], off
	global_load_dwordx4 v[206:209], v[246:247], off
	v_mad_i64_i32 v[158:159], vcc, s17, v140, 0
	v_lshl_add_u64 v[158:159], v[158:159], 1, v[156:157]
	v_lshl_add_u64 v[246:247], v[158:159], 0, s[100:101]
	global_load_dwordx4 v[210:213], v[158:159], off
	global_load_dwordx4 v[214:217], v[246:247], off
	v_mad_i64_i32 v[158:159], vcc, s17, v142, 0
	v_lshl_add_u64 v[158:159], v[158:159], 1, v[156:157]
	v_lshl_add_u64 v[246:247], v[158:159], 0, s[100:101]
	global_load_dwordx4 v[218:221], v[158:159], off
	global_load_dwordx4 v[222:225], v[246:247], off
	v_mad_i64_i32 v[158:159], vcc, s17, v144, 0
	v_lshl_add_u64 v[158:159], v[158:159], 1, v[156:157]
	v_lshl_add_u64 v[246:247], v[158:159], 0, s[100:101]
	global_load_dwordx4 v[226:229], v[158:159], off
	global_load_dwordx4 v[230:233], v[246:247], off
	v_mad_i64_i32 v[158:159], vcc, s17, v146, 0
	v_lshl_add_u64 v[158:159], v[158:159], 1, v[156:157]
	v_lshl_add_u64 v[246:247], v[158:159], 0, s[100:101]
	global_load_dwordx4 v[160:163], v[158:159], off
	global_load_dwordx4 v[164:167], v[246:247], off
	s_waitcnt vmcnt(10)
	v_mad_i64_i32 v[248:249], vcc, s17, v134, 0
	v_lshl_add_u64 v[248:249], v[248:249], 1, v[156:157]
	v_lshlrev_b32_e32 v168, 16, v194
	v_and_b32_e32 v169, 0xffff0000, v194
	v_lshlrev_b32_e32 v170, 16, v198
	v_and_b32_e32 v171, 0xffff0000, v198
	v_lshlrev_b32_e32 v172, 16, v195
	v_and_b32_e32 v173, 0xffff0000, v195
	v_lshlrev_b32_e32 v174, 16, v199
	v_and_b32_e32 v175, 0xffff0000, v199
	v_pk_fma_f32 v[168:169], v[178:179], v[170:171], v[168:169]
	v_pk_fma_f32 v[172:173], v[180:181], v[174:175], v[172:173]
	v_pk_fma_f32 v[124:125], v[186:187], v[124:125], v[168:169]
	v_pk_fma_f32 v[126:127], v[188:189], v[126:127], v[172:173]
	v_lshlrev_b32_e32 v168, 16, v196
	v_and_b32_e32 v169, 0xffff0000, v196
	v_lshlrev_b32_e32 v170, 16, v200
	v_and_b32_e32 v171, 0xffff0000, v200
	v_lshlrev_b32_e32 v172, 16, v197
	v_and_b32_e32 v173, 0xffff0000, v197
	v_lshlrev_b32_e32 v174, 16, v201
	v_and_b32_e32 v175, 0xffff0000, v201
	v_pk_fma_f32 v[168:169], v[182:183], v[170:171], v[168:169]
	v_pk_fma_f32 v[172:173], v[184:185], v[174:175], v[172:173]
	v_pk_fma_f32 v[120:121], v[190:191], v[120:121], v[168:169]
	v_pk_fma_f32 v[122:123], v[192:193], v[122:123], v[172:173]
	s_nop 0
	v_cvt_pk_bf16_f32 v234, v124, v125
	v_cvt_pk_bf16_f32 v235, v126, v127
	v_cvt_pk_bf16_f32 v236, v120, v121
	v_cvt_pk_bf16_f32 v237, v122, v123
	global_store_dwordx4 v[248:249], v[234:237], off
	v_mad_i64_i32 v[158:159], vcc, s17, v148, 0
	v_lshl_add_u64 v[158:159], v[158:159], 1, v[156:157]
	v_lshl_add_u64 v[246:247], v[158:159], 0, s[100:101]
	global_load_dwordx4 v[194:197], v[158:159], off
	global_load_dwordx4 v[198:201], v[246:247], off
	s_waitcnt vmcnt(11)
	v_mad_i64_i32 v[248:249], vcc, s17, v138, 0
	v_lshl_add_u64 v[248:249], v[248:249], 1, v[156:157]
	v_lshlrev_b32_e32 v168, 16, v202
	v_and_b32_e32 v169, 0xffff0000, v202
	v_lshlrev_b32_e32 v170, 16, v206
	v_and_b32_e32 v171, 0xffff0000, v206
	v_lshlrev_b32_e32 v172, 16, v203
	v_and_b32_e32 v173, 0xffff0000, v203
	v_lshlrev_b32_e32 v174, 16, v207
	v_and_b32_e32 v175, 0xffff0000, v207
	v_pk_fma_f32 v[168:169], v[178:179], v[170:171], v[168:169]
	v_pk_fma_f32 v[172:173], v[180:181], v[174:175], v[172:173]
	v_pk_fma_f32 v[116:117], v[186:187], v[116:117], v[168:169]
	v_pk_fma_f32 v[118:119], v[188:189], v[118:119], v[172:173]
	v_lshlrev_b32_e32 v168, 16, v204
	v_and_b32_e32 v169, 0xffff0000, v204
	v_lshlrev_b32_e32 v170, 16, v208
	v_and_b32_e32 v171, 0xffff0000, v208
	v_lshlrev_b32_e32 v172, 16, v205
	v_and_b32_e32 v173, 0xffff0000, v205
	v_lshlrev_b32_e32 v174, 16, v209
	v_and_b32_e32 v175, 0xffff0000, v209
	v_pk_fma_f32 v[168:169], v[182:183], v[170:171], v[168:169]
	v_pk_fma_f32 v[172:173], v[184:185], v[174:175], v[172:173]
	v_pk_fma_f32 v[112:113], v[190:191], v[112:113], v[168:169]
	v_pk_fma_f32 v[114:115], v[192:193], v[114:115], v[172:173]
	s_nop 0
	v_cvt_pk_bf16_f32 v234, v116, v117
	v_cvt_pk_bf16_f32 v235, v118, v119
	v_cvt_pk_bf16_f32 v236, v112, v113
	v_cvt_pk_bf16_f32 v237, v114, v115
	global_store_dwordx4 v[248:249], v[234:237], off
	v_mad_i64_i32 v[158:159], vcc, s17, v150, 0
	v_lshl_add_u64 v[158:159], v[158:159], 1, v[156:157]
	v_lshl_add_u64 v[246:247], v[158:159], 0, s[100:101]
	global_load_dwordx4 v[202:205], v[158:159], off
	global_load_dwordx4 v[206:209], v[246:247], off
	s_waitcnt vmcnt(12)
; #define LAS __attribute__((address_space(3)))
; __device__ __forceinline__ unsigned cvt_pk_bf16(float lo, float hi) { const f32x2 v = {lo, hi}; return __builtin_bit_cast(unsigned, __builtin_convertvector(v, bf16x2_t)); }
; __device__ __forceinline__ float bf_lo(unsigned u) { return __uint_as_float(u << 16); }
; __device__ __forceinline__ float bf_hi(unsigned u) { return __uint_as_float(u & 0xffff0000u); }
;     template <class Sched> __device__ __forceinline__ void operator()(const f32x4 (&acc)[2][2][4][2], const Unit& u, const Sched& S, int wr, int wc, int fr, int fq) const {
;     ...
;                 for (int m = 0; m < 4; ++m) { bf16_t* rowp = base + (size_t)(rl0 + ai * HALF + m * 16) * ldo + cl0;
; #pragma unroll
;                     for (int bj = 0; bj < 2; ++bj) { const f32x4 v0 = acc[ai][bj][m][0], v1 = acc[ai][bj][m][1];
;                         u32x4 w; w.x = cvt_pk_bf16(v0[0], v0[1]); w.y = cvt_pk_bf16(v0[2], v0[3]); w.z = cvt_pk_bf16(v1[0], v1[1]); w.w = cvt_pk_bf16(v1[2], v1[3]);
;                         *(u32x4*)(rowp + bj * HALF) = w; } }
; __device__ __forceinline__ void norm_mod_phase(Frame& F, int L, const float* gvec, int sh_chunk, int nrows, const float* pg, const float* pg2, const float* xlat, const float* xctx) {
;     ...
;         if (h2) {
;             const LAS f32x4* gq = vq + 3 * (D / 4); u32x2* xw_ = (u32x2*)((bf16_t*)(F.ws + WS_XB) + (size_t)r * D) + lane;
; #pragma unroll
;             for (int j = 0; j < 8; ++j) { const u32x2 yy = aux[1][j]; const f32x4 y4 = {bf_lo(yy.x), bf_hi(yy.x), bf_lo(yy.y), bf_hi(yy.y)}; v[j] += gq[64 * j] * y4; u32x2 w; w.x = cvt_pk_bf16(v[j].x, v[j].y); w.y = cvt_pk_bf16(v[j].z, v[j].w); xw_[64 * j] = w; }
;         }
	v_mad_i64_i32 v[248:249], vcc, s17, v140, 0
	v_lshl_add_u64 v[248:249], v[248:249], 1, v[156:157]
	v_lshlrev_b32_e32 v168, 16, v210
	v_and_b32_e32 v169, 0xffff0000, v210
	v_lshlrev_b32_e32 v170, 16, v214
	v_and_b32_e32 v171, 0xffff0000, v214
	v_lshlrev_b32_e32 v172, 16, v211
	v_and_b32_e32 v173, 0xffff0000, v211
	v_lshlrev_b32_e32 v174, 16, v215
	v_and_b32_e32 v175, 0xffff0000, v215
	v_pk_fma_f32 v[168:169], v[178:179], v[170:171], v[168:169]
	v_pk_fma_f32 v[172:173], v[180:181], v[174:175], v[172:173]
	v_pk_fma_f32 v[100:101], v[186:187], v[100:101], v[168:169]
	v_pk_fma_f32 v[102:103], v[188:189], v[102:103], v[172:173]
	v_lshlrev_b32_e32 v168, 16, v212
	v_and_b32_e32 v169, 0xffff0000, v212
	v_lshlrev_b32_e32 v170, 16, v216
	v_and_b32_e32 v171, 0xffff0000, v216
	v_lshlrev_b32_e32 v172, 16, v213
	v_and_b32_e32 v173, 0xffff0000, v213
	v_lshlrev_b32_e32 v174, 16, v217
	v_and_b32_e32 v175, 0xffff0000, v217
	v_pk_fma_f32 v[168:169], v[182:183], v[170:171], v[168:169]
	v_pk_fma_f32 v[172:173], v[184:185], v[174:175], v[172:173]
	v_pk_fma_f32 v[96:97], v[190:191], v[96:97], v[168:169]
	v_pk_fma_f32 v[98:99], v[192:193], v[98:99], v[172:173]
	s_nop 0
	v_cvt_pk_bf16_f32 v234, v100, v101
	v_cvt_pk_bf16_f32 v235, v102, v103
	v_cvt_pk_bf16_f32 v236, v96, v97
	v_cvt_pk_bf16_f32 v237, v98, v99
	global_store_dwordx4 v[248:249], v[234:237], off
	s_waitcnt vmcnt(11)
	v_mad_i64_i32 v[248:249], vcc, s17, v142, 0
	v_lshl_add_u64 v[248:249], v[248:249], 1, v[156:157]
	v_lshlrev_b32_e32 v168, 16, v218
	v_and_b32_e32 v169, 0xffff0000, v218
	v_lshlrev_b32_e32 v170, 16, v222
	v_and_b32_e32 v171, 0xffff0000, v222
	v_lshlrev_b32_e32 v172, 16, v219
	v_and_b32_e32 v173, 0xffff0000, v219
	v_lshlrev_b32_e32 v174, 16, v223
	v_and_b32_e32 v175, 0xffff0000, v223
	v_pk_fma_f32 v[168:169], v[178:179], v[170:171], v[168:169]
	v_pk_fma_f32 v[172:173], v[180:181], v[174:175], v[172:173]
	v_pk_fma_f32 v[84:85], v[186:187], v[84:85], v[168:169]
	v_pk_fma_f32 v[86:87], v[188:189], v[86:87], v[172:173]
	v_lshlrev_b32_e32 v168, 16, v220
	v_and_b32_e32 v169, 0xffff0000, v220
	v_lshlrev_b32_e32 v170, 16, v224
	v_and_b32_e32 v171, 0xffff0000, v224
	v_lshlrev_b32_e32 v172, 16, v221
	v_and_b32_e32 v173, 0xffff0000, v221
	v_lshlrev_b32_e32 v174, 16, v225
	v_and_b32_e32 v175, 0xffff0000, v225
	v_pk_fma_f32 v[168:169], v[182:183], v[170:171], v[168:169]
	v_pk_fma_f32 v[172:173], v[184:185], v[174:175], v[172:173]
	v_pk_fma_f32 v[80:81], v[190:191], v[80:81], v[168:169]
	v_pk_fma_f32 v[82:83], v[192:193], v[82:83], v[172:173]
	s_nop 0
	v_cvt_pk_bf16_f32 v234, v84, v85
	v_cvt_pk_bf16_f32 v235, v86, v87
	v_cvt_pk_bf16_f32 v236, v80, v81
	v_cvt_pk_bf16_f32 v237, v82, v83
	global_store_dwordx4 v[248:249], v[234:237], off
	s_waitcnt vmcnt(10)
	v_mad_i64_i32 v[248:249], vcc, s17, v144, 0
	v_lshl_add_u64 v[248:249], v[248:249], 1, v[156:157]
	v_lshlrev_b32_e32 v168, 16, v226
	v_and_b32_e32 v169, 0xffff0000, v226
	v_lshlrev_b32_e32 v170, 16, v230
	v_and_b32_e32 v171, 0xffff0000, v230
	v_lshlrev_b32_e32 v172, 16, v227
	v_and_b32_e32 v173, 0xffff0000, v227
	v_lshlrev_b32_e32 v174, 16, v231
	v_and_b32_e32 v175, 0xffff0000, v231
	v_pk_fma_f32 v[168:169], v[178:179], v[170:171], v[168:169]
	v_pk_fma_f32 v[172:173], v[180:181], v[174:175], v[172:173]
	v_pk_fma_f32 v[60:61], v[186:187], v[60:61], v[168:169]
	v_pk_fma_f32 v[62:63], v[188:189], v[62:63], v[172:173]
	v_lshlrev_b32_e32 v168, 16, v228
	v_and_b32_e32 v169, 0xffff0000, v228
	v_lshlrev_b32_e32 v170, 16, v232
	v_and_b32_e32 v171, 0xffff0000, v232
	v_lshlrev_b32_e32 v172, 16, v229
	v_and_b32_e32 v173, 0xffff0000, v229
	v_lshlrev_b32_e32 v174, 16, v233
	v_and_b32_e32 v175, 0xffff0000, v233
	v_pk_fma_f32 v[168:169], v[182:183], v[170:171], v[168:169]
	v_pk_fma_f32 v[172:173], v[184:185], v[174:175], v[172:173]
	v_pk_fma_f32 v[56:57], v[190:191], v[56:57], v[168:169]
	v_pk_fma_f32 v[58:59], v[192:193], v[58:59], v[172:173]
	s_nop 0
	v_cvt_pk_bf16_f32 v234, v60, v61
	v_cvt_pk_bf16_f32 v235, v62, v63
	v_cvt_pk_bf16_f32 v236, v56, v57
	v_cvt_pk_bf16_f32 v237, v58, v59
	global_store_dwordx4 v[248:249], v[234:237], off
	s_waitcnt vmcnt(9)
	v_mad_i64_i32 v[248:249], vcc, s17, v146, 0
	v_lshl_add_u64 v[248:249], v[248:249], 1, v[156:157]
	v_lshlrev_b32_e32 v168, 16, v160
	v_and_b32_e32 v169, 0xffff0000, v160
	v_lshlrev_b32_e32 v170, 16, v164
	v_and_b32_e32 v171, 0xffff0000, v164
	v_lshlrev_b32_e32 v172, 16, v161
	v_and_b32_e32 v173, 0xffff0000, v161
	v_lshlrev_b32_e32 v174, 16, v165
	v_and_b32_e32 v175, 0xffff0000, v165
	v_pk_fma_f32 v[168:169], v[178:179], v[170:171], v[168:169]
	v_pk_fma_f32 v[172:173], v[180:181], v[174:175], v[172:173]
	v_pk_fma_f32 v[52:53], v[186:187], v[52:53], v[168:169]
	v_pk_fma_f32 v[54:55], v[188:189], v[54:55], v[172:173]
	v_lshlrev_b32_e32 v168, 16, v162
	v_and_b32_e32 v169, 0xffff0000, v162
	v_lshlrev_b32_e32 v170, 16, v166
	v_and_b32_e32 v171, 0xffff0000, v166
	v_lshlrev_b32_e32 v172, 16, v163
	v_and_b32_e32 v173, 0xffff0000, v163
	v_lshlrev_b32_e32 v174, 16, v167
	v_and_b32_e32 v175, 0xffff0000, v167
	v_pk_fma_f32 v[168:169], v[182:183], v[170:171], v[168:169]
	v_pk_fma_f32 v[172:173], v[184:185], v[174:175], v[172:173]
	v_pk_fma_f32 v[48:49], v[190:191], v[48:49], v[168:169]
	v_pk_fma_f32 v[50:51], v[192:193], v[50:51], v[172:173]
	s_nop 0
	v_cvt_pk_bf16_f32 v234, v52, v53
	v_cvt_pk_bf16_f32 v235, v54, v55
	v_cvt_pk_bf16_f32 v236, v48, v49
	v_cvt_pk_bf16_f32 v237, v50, v51
	global_store_dwordx4 v[248:249], v[234:237], off
	s_waitcnt vmcnt(7)
; #define LAS __attribute__((address_space(3)))
; __device__ __forceinline__ unsigned cvt_pk_bf16(float lo, float hi) { const f32x2 v = {lo, hi}; return __builtin_bit_cast(unsigned, __builtin_convertvector(v, bf16x2_t)); }
; __device__ __forceinline__ float bf_lo(unsigned u) { return __uint_as_float(u << 16); }
; __device__ __forceinline__ float bf_hi(unsigned u) { return __uint_as_float(u & 0xffff0000u); }
;     template <class Sched> __device__ __forceinline__ void operator()(const f32x4 (&acc)[2][2][4][2], const Unit& u, const Sched& S, int wr, int wc, int fr, int fq) const {
;     ...
;                 for (int m = 0; m < 4; ++m) { bf16_t* rowp = base + (size_t)(rl0 + ai * HALF + m * 16) * ldo + cl0;
; #pragma unroll
;                     for (int bj = 0; bj < 2; ++bj) { const f32x4 v0 = acc[ai][bj][m][0], v1 = acc[ai][bj][m][1];
;                         u32x4 w; w.x = cvt_pk_bf16(v0[0], v0[1]); w.y = cvt_pk_bf16(v0[2], v0[3]); w.z = cvt_pk_bf16(v1[0], v1[1]); w.w = cvt_pk_bf16(v1[2], v1[3]);
;                         *(u32x4*)(rowp + bj * HALF) = w; } }
; __device__ __forceinline__ void norm_mod_phase(Frame& F, int L, const float* gvec, int sh_chunk, int nrows, const float* pg, const float* pg2, const float* xlat, const float* xctx) {
;     ...
;         if (h2) {
;             const LAS f32x4* gq = vq + 3 * (D / 4); u32x2* xw_ = (u32x2*)((bf16_t*)(F.ws + WS_XB) + (size_t)r * D) + lane;
; #pragma unroll
;             for (int j = 0; j < 8; ++j) { const u32x2 yy = aux[1][j]; const f32x4 y4 = {bf_lo(yy.x), bf_hi(yy.x), bf_lo(yy.y), bf_hi(yy.y)}; v[j] += gq[64 * j] * y4; u32x2 w; w.x = cvt_pk_bf16(v[j].x, v[j].y); w.y = cvt_pk_bf16(v[j].z, v[j].w); xw_[64 * j] = w; }
;         }
	v_mad_i64_i32 v[248:249], vcc, s17, v148, 0
	v_lshl_add_u64 v[248:249], v[248:249], 1, v[156:157]
	v_lshlrev_b32_e32 v168, 16, v194
	v_and_b32_e32 v169, 0xffff0000, v194
	v_lshlrev_b32_e32 v170, 16, v198
	v_and_b32_e32 v171, 0xffff0000, v198
	v_lshlrev_b32_e32 v172, 16, v195
	v_and_b32_e32 v173, 0xffff0000, v195
	v_lshlrev_b32_e32 v174, 16, v199
	v_and_b32_e32 v175, 0xffff0000, v199
	v_pk_fma_f32 v[168:169], v[178:179], v[170:171], v[168:169]
	v_pk_fma_f32 v[172:173], v[180:181], v[174:175], v[172:173]
	v_pk_fma_f32 v[36:37], v[186:187], v[36:37], v[168:169]
	v_pk_fma_f32 v[38:39], v[188:189], v[38:39], v[172:173]
	v_lshlrev_b32_e32 v168, 16, v196
	v_and_b32_e32 v169, 0xffff0000, v196
	v_lshlrev_b32_e32 v170, 16, v200
	v_and_b32_e32 v171, 0xffff0000, v200
	v_lshlrev_b32_e32 v172, 16, v197
	v_and_b32_e32 v173, 0xffff0000, v197
	v_lshlrev_b32_e32 v174, 16, v201
	v_and_b32_e32 v175, 0xffff0000, v201
	v_pk_fma_f32 v[168:169], v[182:183], v[170:171], v[168:169]
	v_pk_fma_f32 v[172:173], v[184:185], v[174:175], v[172:173]
	v_pk_fma_f32 v[32:33], v[190:191], v[32:33], v[168:169]
	v_pk_fma_f32 v[34:35], v[192:193], v[34:35], v[172:173]
	s_nop 0
	v_cvt_pk_bf16_f32 v234, v36, v37
	v_cvt_pk_bf16_f32 v235, v38, v39
	v_cvt_pk_bf16_f32 v236, v32, v33
	v_cvt_pk_bf16_f32 v237, v34, v35
	global_store_dwordx4 v[248:249], v[234:237], off
	s_waitcnt vmcnt(5)
	v_mad_i64_i32 v[248:249], vcc, s17, v150, 0
	v_lshl_add_u64 v[248:249], v[248:249], 1, v[156:157]
	v_lshlrev_b32_e32 v168, 16, v202
	v_and_b32_e32 v169, 0xffff0000, v202
	v_lshlrev_b32_e32 v170, 16, v206
	v_and_b32_e32 v171, 0xffff0000, v206
	v_lshlrev_b32_e32 v172, 16, v203
	v_and_b32_e32 v173, 0xffff0000, v203
	v_lshlrev_b32_e32 v174, 16, v207
	v_and_b32_e32 v175, 0xffff0000, v207
	v_pk_fma_f32 v[168:169], v[178:179], v[170:171], v[168:169]
	v_pk_fma_f32 v[172:173], v[180:181], v[174:175], v[172:173]
	v_pk_fma_f32 v[20:21], v[186:187], v[20:21], v[168:169]
	v_pk_fma_f32 v[22:23], v[188:189], v[22:23], v[172:173]
	v_lshlrev_b32_e32 v168, 16, v204
	v_and_b32_e32 v169, 0xffff0000, v204
	v_lshlrev_b32_e32 v170, 16, v208
	v_and_b32_e32 v171, 0xffff0000, v208
	v_lshlrev_b32_e32 v172, 16, v205
	v_and_b32_e32 v173, 0xffff0000, v205
	v_lshlrev_b32_e32 v174, 16, v209
	v_and_b32_e32 v175, 0xffff0000, v209
	v_pk_fma_f32 v[168:169], v[182:183], v[170:171], v[168:169]
	v_pk_fma_f32 v[172:173], v[184:185], v[174:175], v[172:173]
	v_pk_fma_f32 v[16:17], v[190:191], v[16:17], v[168:169]
	v_pk_fma_f32 v[18:19], v[192:193], v[18:19], v[172:173]
	s_nop 0
	v_cvt_pk_bf16_f32 v234, v20, v21
	v_cvt_pk_bf16_f32 v235, v22, v23
	v_cvt_pk_bf16_f32 v236, v16, v17
	v_cvt_pk_bf16_f32 v237, v18, v19
	global_store_dwordx4 v[248:249], v[234:237], off
	v_lshl_add_u64 v[158:159], v[136:137], 2, s[30:31]
	global_load_dwordx4 v[178:181], v[158:159], off offset:512
	global_load_dwordx4 v[182:185], v[158:159], off offset:528
	v_lshl_add_u64 v[246:247], v[136:137], 2, s[34:35]
	global_load_dwordx4 v[186:189], v[246:247], off offset:512
	global_load_dwordx4 v[190:193], v[246:247], off offset:528
	v_mad_i64_i32 v[158:159], vcc, s17, v134, 0
	v_lshl_add_u64 v[158:159], v[158:159], 1, v[156:157]
	v_lshl_add_u64 v[246:247], v[158:159], 0, s[100:101]
	global_load_dwordx4 v[194:197], v[158:159], off offset:256
	global_load_dwordx4 v[198:201], v[246:247], off offset:256
	v_mad_i64_i32 v[158:159], vcc, s17, v138, 0
	v_lshl_add_u64 v[158:159], v[158:159], 1, v[156:157]
	v_lshl_add_u64 v[246:247], v[158:159], 0, s[100:101]
	global_load_dwordx4 v[202:205], v[158:159], off offset:256
	global_load_dwordx4 v[206:209], v[246:247], off offset:256
	v_mad_i64_i32 v[158:159], vcc, s17, v140, 0
	v_lshl_add_u64 v[158:159], v[158:159], 1, v[156:157]
	v_lshl_add_u64 v[246:247], v[158:159], 0, s[100:101]
	global_load_dwordx4 v[210:213], v[158:159], off offset:256
	global_load_dwordx4 v[214:217], v[246:247], off offset:256
	v_mad_i64_i32 v[158:159], vcc, s17, v142, 0
	v_lshl_add_u64 v[158:159], v[158:159], 1, v[156:157]
	v_lshl_add_u64 v[246:247], v[158:159], 0, s[100:101]
	global_load_dwordx4 v[218:221], v[158:159], off offset:256
	global_load_dwordx4 v[222:225], v[246:247], off offset:256
	v_mad_i64_i32 v[158:159], vcc, s17, v144, 0
	v_lshl_add_u64 v[158:159], v[158:159], 1, v[156:157]
	v_lshl_add_u64 v[246:247], v[158:159], 0, s[100:101]
	global_load_dwordx4 v[226:229], v[158:159], off offset:256
	global_load_dwordx4 v[230:233], v[246:247], off offset:256
	v_mad_i64_i32 v[158:159], vcc, s17, v146, 0
	v_lshl_add_u64 v[158:159], v[158:159], 1, v[156:157]
	v_lshl_add_u64 v[246:247], v[158:159], 0, s[100:101]
	global_load_dwordx4 v[160:163], v[158:159], off offset:256
	global_load_dwordx4 v[164:167], v[246:247], off offset:256
	s_waitcnt vmcnt(10)
	v_mad_i64_i32 v[248:249], vcc, s17, v134, 0
	v_lshl_add_u64 v[248:249], v[248:249], 1, v[156:157]
	v_lshlrev_b32_e32 v168, 16, v194
	v_and_b32_e32 v169, 0xffff0000, v194
	v_lshlrev_b32_e32 v170, 16, v198
	v_and_b32_e32 v171, 0xffff0000, v198
	v_lshlrev_b32_e32 v172, 16, v195
	v_and_b32_e32 v173, 0xffff0000, v195
	v_lshlrev_b32_e32 v174, 16, v199
	v_and_b32_e32 v175, 0xffff0000, v199
	v_pk_fma_f32 v[168:169], v[178:179], v[170:171], v[168:169]
	v_pk_fma_f32 v[172:173], v[180:181], v[174:175], v[172:173]
	v_pk_fma_f32 v[108:109], v[186:187], v[108:109], v[168:169]
	v_pk_fma_f32 v[110:111], v[188:189], v[110:111], v[172:173]
	v_lshlrev_b32_e32 v168, 16, v196
	v_and_b32_e32 v169, 0xffff0000, v196
	v_lshlrev_b32_e32 v170, 16, v200
	v_and_b32_e32 v171, 0xffff0000, v200
	v_lshlrev_b32_e32 v172, 16, v197
	v_and_b32_e32 v173, 0xffff0000, v197
	v_lshlrev_b32_e32 v174, 16, v201
	v_and_b32_e32 v175, 0xffff0000, v201
	v_pk_fma_f32 v[168:169], v[182:183], v[170:171], v[168:169]
	v_pk_fma_f32 v[172:173], v[184:185], v[174:175], v[172:173]
	v_pk_fma_f32 v[104:105], v[190:191], v[104:105], v[168:169]
	v_pk_fma_f32 v[106:107], v[192:193], v[106:107], v[172:173]
	s_nop 0
	v_cvt_pk_bf16_f32 v234, v108, v109
	v_cvt_pk_bf16_f32 v235, v110, v111
	v_cvt_pk_bf16_f32 v236, v104, v105
	v_cvt_pk_bf16_f32 v237, v106, v107
	global_store_dwordx4 v[248:249], v[234:237], off offset:256
	v_mad_i64_i32 v[158:159], vcc, s17, v148, 0
	v_lshl_add_u64 v[158:159], v[158:159], 1, v[156:157]
	v_lshl_add_u64 v[246:247], v[158:159], 0, s[100:101]
	global_load_dwordx4 v[194:197], v[158:159], off offset:256
	global_load_dwordx4 v[198:201], v[246:247], off offset:256
	s_waitcnt vmcnt(11)
; #define LAS __attribute__((address_space(3)))
; __device__ __forceinline__ unsigned cvt_pk_bf16(float lo, float hi) { const f32x2 v = {lo, hi}; return __builtin_bit_cast(unsigned, __builtin_convertvector(v, bf16x2_t)); }
; __device__ __forceinline__ float bf_lo(unsigned u) { return __uint_as_float(u << 16); }
; __device__ __forceinline__ float bf_hi(unsigned u) { return __uint_as_float(u & 0xffff0000u); }
;     template <class Sched> __device__ __forceinline__ void operator()(const f32x4 (&acc)[2][2][4][2], const Unit& u, const Sched& S, int wr, int wc, int fr, int fq) const {
;     ...
;                 for (int m = 0; m < 4; ++m) { bf16_t* rowp = base + (size_t)(rl0 + ai * HALF + m * 16) * ldo + cl0;
; #pragma unroll
;                     for (int bj = 0; bj < 2; ++bj) { const f32x4 v0 = acc[ai][bj][m][0], v1 = acc[ai][bj][m][1];
;                         u32x4 w; w.x = cvt_pk_bf16(v0[0], v0[1]); w.y = cvt_pk_bf16(v0[2], v0[3]); w.z = cvt_pk_bf16(v1[0], v1[1]); w.w = cvt_pk_bf16(v1[2], v1[3]);
;                         *(u32x4*)(rowp + bj * HALF) = w; } }
; __device__ __forceinline__ void norm_mod_phase(Frame& F, int L, const float* gvec, int sh_chunk, int nrows, const float* pg, const float* pg2, const float* xlat, const float* xctx) {
;     ...
;         if (h2) {
;             const LAS f32x4* gq = vq + 3 * (D / 4); u32x2* xw_ = (u32x2*)((bf16_t*)(F.ws + WS_XB) + (size_t)r * D) + lane;
; #pragma unroll
;             for (int j = 0; j < 8; ++j) { const u32x2 yy = aux[1][j]; const f32x4 y4 = {bf_lo(yy.x), bf_hi(yy.x), bf_lo(yy.y), bf_hi(yy.y)}; v[j] += gq[64 * j] * y4; u32x2 w; w.x = cvt_pk_bf16(v[j].x, v[j].y); w.y = cvt_pk_bf16(v[j].z, v[j].w); xw_[64 * j] = w; }
;         }
	v_mad_i64_i32 v[248:249], vcc, s17, v138, 0
	v_lshl_add_u64 v[248:249], v[248:249], 1, v[156:157]
	v_lshlrev_b32_e32 v168, 16, v202
	v_and_b32_e32 v169, 0xffff0000, v202
	v_lshlrev_b32_e32 v170, 16, v206
	v_and_b32_e32 v171, 0xffff0000, v206
	v_lshlrev_b32_e32 v172, 16, v203
	v_and_b32_e32 v173, 0xffff0000, v203
	v_lshlrev_b32_e32 v174, 16, v207
	v_and_b32_e32 v175, 0xffff0000, v207
	v_pk_fma_f32 v[168:169], v[178:179], v[170:171], v[168:169]
	v_pk_fma_f32 v[172:173], v[180:181], v[174:175], v[172:173]
	v_pk_fma_f32 v[92:93], v[186:187], v[92:93], v[168:169]
	v_pk_fma_f32 v[94:95], v[188:189], v[94:95], v[172:173]
	v_lshlrev_b32_e32 v168, 16, v204
	v_and_b32_e32 v169, 0xffff0000, v204
	v_lshlrev_b32_e32 v170, 16, v208
	v_and_b32_e32 v171, 0xffff0000, v208
	v_lshlrev_b32_e32 v172, 16, v205
	v_and_b32_e32 v173, 0xffff0000, v205
	v_lshlrev_b32_e32 v174, 16, v209
	v_and_b32_e32 v175, 0xffff0000, v209
	v_pk_fma_f32 v[168:169], v[182:183], v[170:171], v[168:169]
	v_pk_fma_f32 v[172:173], v[184:185], v[174:175], v[172:173]
	v_pk_fma_f32 v[88:89], v[190:191], v[88:89], v[168:169]
	v_pk_fma_f32 v[90:91], v[192:193], v[90:91], v[172:173]
	s_nop 0
	v_cvt_pk_bf16_f32 v234, v92, v93
	v_cvt_pk_bf16_f32 v235, v94, v95
	v_cvt_pk_bf16_f32 v236, v88, v89
	v_cvt_pk_bf16_f32 v237, v90, v91
	global_store_dwordx4 v[248:249], v[234:237], off offset:256
	v_mad_i64_i32 v[158:159], vcc, s17, v150, 0
	v_lshl_add_u64 v[158:159], v[158:159], 1, v[156:157]
	v_lshl_add_u64 v[246:247], v[158:159], 0, s[100:101]
	global_load_dwordx4 v[202:205], v[158:159], off offset:256
	global_load_dwordx4 v[206:209], v[246:247], off offset:256
	s_waitcnt vmcnt(12)
	v_mad_i64_i32 v[248:249], vcc, s17, v140, 0
	v_lshl_add_u64 v[248:249], v[248:249], 1, v[156:157]
	v_lshlrev_b32_e32 v168, 16, v210
	v_and_b32_e32 v169, 0xffff0000, v210
	v_lshlrev_b32_e32 v170, 16, v214
	v_and_b32_e32 v171, 0xffff0000, v214
	v_lshlrev_b32_e32 v172, 16, v211
	v_and_b32_e32 v173, 0xffff0000, v211
	v_lshlrev_b32_e32 v174, 16, v215
	v_and_b32_e32 v175, 0xffff0000, v215
	v_pk_fma_f32 v[168:169], v[178:179], v[170:171], v[168:169]
	v_pk_fma_f32 v[172:173], v[180:181], v[174:175], v[172:173]
	v_pk_fma_f32 v[76:77], v[186:187], v[76:77], v[168:169]
	v_pk_fma_f32 v[78:79], v[188:189], v[78:79], v[172:173]
	v_lshlrev_b32_e32 v168, 16, v212
	v_and_b32_e32 v169, 0xffff0000, v212
	v_lshlrev_b32_e32 v170, 16, v216
	v_and_b32_e32 v171, 0xffff0000, v216
	v_lshlrev_b32_e32 v172, 16, v213
	v_and_b32_e32 v173, 0xffff0000, v213
	v_lshlrev_b32_e32 v174, 16, v217
	v_and_b32_e32 v175, 0xffff0000, v217
	v_pk_fma_f32 v[168:169], v[182:183], v[170:171], v[168:169]
	v_pk_fma_f32 v[172:173], v[184:185], v[174:175], v[172:173]
	v_pk_fma_f32 v[72:73], v[190:191], v[72:73], v[168:169]
	v_pk_fma_f32 v[74:75], v[192:193], v[74:75], v[172:173]
	s_nop 0
	v_cvt_pk_bf16_f32 v234, v76, v77
	v_cvt_pk_bf16_f32 v235, v78, v79
	v_cvt_pk_bf16_f32 v236, v72, v73
	v_cvt_pk_bf16_f32 v237, v74, v75
	global_store_dwordx4 v[248:249], v[234:237], off offset:256
	s_waitcnt vmcnt(11)
	v_mad_i64_i32 v[248:249], vcc, s17, v142, 0
	v_lshl_add_u64 v[248:249], v[248:249], 1, v[156:157]
	v_lshlrev_b32_e32 v168, 16, v218
	v_and_b32_e32 v169, 0xffff0000, v218
	v_lshlrev_b32_e32 v170, 16, v222
	v_and_b32_e32 v171, 0xffff0000, v222
	v_lshlrev_b32_e32 v172, 16, v219
	v_and_b32_e32 v173, 0xffff0000, v219
	v_lshlrev_b32_e32 v174, 16, v223
	v_and_b32_e32 v175, 0xffff0000, v223
	v_pk_fma_f32 v[168:169], v[178:179], v[170:171], v[168:169]
	v_pk_fma_f32 v[172:173], v[180:181], v[174:175], v[172:173]
	v_pk_fma_f32 v[68:69], v[186:187], v[68:69], v[168:169]
	v_pk_fma_f32 v[70:71], v[188:189], v[70:71], v[172:173]
	v_lshlrev_b32_e32 v168, 16, v220
	v_and_b32_e32 v169, 0xffff0000, v220
	v_lshlrev_b32_e32 v170, 16, v224
	v_and_b32_e32 v171, 0xffff0000, v224
	v_lshlrev_b32_e32 v172, 16, v221
	v_and_b32_e32 v173, 0xffff0000, v221
	v_lshlrev_b32_e32 v174, 16, v225
	v_and_b32_e32 v175, 0xffff0000, v225
	v_pk_fma_f32 v[168:169], v[182:183], v[170:171], v[168:169]
	v_pk_fma_f32 v[172:173], v[184:185], v[174:175], v[172:173]
	v_pk_fma_f32 v[64:65], v[190:191], v[64:65], v[168:169]
	v_pk_fma_f32 v[66:67], v[192:193], v[66:67], v[172:173]
	s_nop 0
	v_cvt_pk_bf16_f32 v234, v68, v69
	v_cvt_pk_bf16_f32 v235, v70, v71
	v_cvt_pk_bf16_f32 v236, v64, v65
	v_cvt_pk_bf16_f32 v237, v66, v67
	global_store_dwordx4 v[248:249], v[234:237], off offset:256
	s_waitcnt vmcnt(10)
; __device__ __forceinline__ unsigned cvt_pk_bf16(float lo, float hi) { const f32x2 v = {lo, hi}; return __builtin_bit_cast(unsigned, __builtin_convertvector(v, bf16x2_t)); }
;     __device__ __forceinline__ const char* a(const pg8::Unit& u) const { return (const char*)ws + aoff + (size_t)u.pm * 256 * K_ * 2 + (u.kq < 0 ? 0 : u.kq * (K_ / 4) * 2); }
;     __device__ __forceinline__ const char* b(const pg8::Unit& u) const { return (const char*)ws + boff + (size_t)u.pn * 256 * K_ * 2 + (u.kq < 0 ? 0 : u.kq * (K_ / 4) * 2); }
;     __device__ __forceinline__ const char* a(const pg8::Unit& u) const { return (const char*)ws + WS_A + (size_t)u.pm * 256 * D * 2; }
;     __device__ __forceinline__ const char* b(const pg8::Unit& u) const { return (const char*)ws + boff + (size_t)u.pn * 256 * D * 2; }
;     __device__ __forceinline__ const char* a(const pg8::Unit& u) const { return (const char*)ws + WS_A + (size_t)u.pm * 256 * D * 2; }
;     __device__ __forceinline__ const char* b(const pg8::Unit& u) const { return (const char*)ws + boff + (size_t)u.pn * 256 * D * 2; }
;     template <class Sched> __device__ __forceinline__ void operator()(const f32x4 (&acc)[2][2][4][2], const Unit& u, const Sched& S, int wr, int wc, int fr, int fq) const {
;     ...
;                 for (int m = 0; m < 4; ++m) { bf16_t* rowp = base + (size_t)(rl0 + ai * HALF + m * 16) * ldo + cl0;
; #pragma unroll
;                     for (int bj = 0; bj < 2; ++bj) { const f32x4 v0 = acc[ai][bj][m][0], v1 = acc[ai][bj][m][1];
;                         u32x4 w; w.x = cvt_pk_bf16(v0[0], v0[1]); w.y = cvt_pk_bf16(v0[2], v0[3]); w.z = cvt_pk_bf16(v1[0], v1[1]); w.w = cvt_pk_bf16(v1[2], v1[3]);
;                         *(u32x4*)(rowp + bj * HALF) = w; } }
; template <class Epi, class Sched, bool ALIGN_EPI>
; __device__ __forceinline__ void gemm_phase(LAS unsigned char* lds, const int wid, const int lda_, const int ldb_, const int K_, const Sched& S, const Epi& E) {
;     ...
;         if (!has_next) break;
; #pragma unroll
;         for (int a = 0; a < 2; ++a)
; #pragma unroll
;             for (int b = 0; b < 2; ++b)
; #pragma unroll
;                 for (int m = 0; m < 4; ++m)
; #pragma unroll
;                     for (int n = 0; n < 2; ++n) acc[a][b][m][n] = (f32x4){0.f, 0.f, 0.f, 0.f};
;         cur = nxt; cA = nA; cB = nB; ++ui;
	v_mad_i64_i32 v[248:249], vcc, s17, v144, 0
	v_lshl_add_u64 v[248:249], v[248:249], 1, v[156:157]
	v_lshlrev_b32_e32 v168, 16, v226
	v_and_b32_e32 v169, 0xffff0000, v226
	v_lshlrev_b32_e32 v170, 16, v230
	v_and_b32_e32 v171, 0xffff0000, v230
	v_lshlrev_b32_e32 v172, 16, v227
	v_and_b32_e32 v173, 0xffff0000, v227
	v_lshlrev_b32_e32 v174, 16, v231
	v_and_b32_e32 v175, 0xffff0000, v231
	v_pk_fma_f32 v[168:169], v[178:179], v[170:171], v[168:169]
	v_pk_fma_f32 v[172:173], v[180:181], v[174:175], v[172:173]
	v_pk_fma_f32 v[44:45], v[186:187], v[44:45], v[168:169]
	v_pk_fma_f32 v[46:47], v[188:189], v[46:47], v[172:173]
	v_lshlrev_b32_e32 v168, 16, v228
	v_and_b32_e32 v169, 0xffff0000, v228
	v_lshlrev_b32_e32 v170, 16, v232
	v_and_b32_e32 v171, 0xffff0000, v232
	v_lshlrev_b32_e32 v172, 16, v229
	v_and_b32_e32 v173, 0xffff0000, v229
	v_lshlrev_b32_e32 v174, 16, v233
	v_and_b32_e32 v175, 0xffff0000, v233
	v_pk_fma_f32 v[168:169], v[182:183], v[170:171], v[168:169]
	v_pk_fma_f32 v[172:173], v[184:185], v[174:175], v[172:173]
	v_pk_fma_f32 v[40:41], v[190:191], v[40:41], v[168:169]
	v_pk_fma_f32 v[42:43], v[192:193], v[42:43], v[172:173]
	s_nop 0
	v_cvt_pk_bf16_f32 v234, v44, v45
	v_cvt_pk_bf16_f32 v235, v46, v47
	v_cvt_pk_bf16_f32 v236, v40, v41
	v_cvt_pk_bf16_f32 v237, v42, v43
	global_store_dwordx4 v[248:249], v[234:237], off offset:256
	s_waitcnt vmcnt(9)
	v_mad_i64_i32 v[248:249], vcc, s17, v146, 0
	v_lshl_add_u64 v[248:249], v[248:249], 1, v[156:157]
	v_lshlrev_b32_e32 v168, 16, v160
	v_and_b32_e32 v169, 0xffff0000, v160
	v_lshlrev_b32_e32 v170, 16, v164
	v_and_b32_e32 v171, 0xffff0000, v164
	v_lshlrev_b32_e32 v172, 16, v161
	v_and_b32_e32 v173, 0xffff0000, v161
	v_lshlrev_b32_e32 v174, 16, v165
	v_and_b32_e32 v175, 0xffff0000, v165
	v_pk_fma_f32 v[168:169], v[178:179], v[170:171], v[168:169]
	v_pk_fma_f32 v[172:173], v[180:181], v[174:175], v[172:173]
	v_pk_fma_f32 v[28:29], v[186:187], v[28:29], v[168:169]
	v_pk_fma_f32 v[30:31], v[188:189], v[30:31], v[172:173]
	v_lshlrev_b32_e32 v168, 16, v162
	v_and_b32_e32 v169, 0xffff0000, v162
	v_lshlrev_b32_e32 v170, 16, v166
	v_and_b32_e32 v171, 0xffff0000, v166
	v_lshlrev_b32_e32 v172, 16, v163
	v_and_b32_e32 v173, 0xffff0000, v163
	v_lshlrev_b32_e32 v174, 16, v167
	v_and_b32_e32 v175, 0xffff0000, v167
	v_pk_fma_f32 v[168:169], v[182:183], v[170:171], v[168:169]
	v_pk_fma_f32 v[172:173], v[184:185], v[174:175], v[172:173]
	v_pk_fma_f32 v[24:25], v[190:191], v[24:25], v[168:169]
	v_pk_fma_f32 v[26:27], v[192:193], v[26:27], v[172:173]
	s_nop 0
	v_cvt_pk_bf16_f32 v234, v28, v29
	v_cvt_pk_bf16_f32 v235, v30, v31
	v_cvt_pk_bf16_f32 v236, v24, v25
	v_cvt_pk_bf16_f32 v237, v26, v27
	global_store_dwordx4 v[248:249], v[234:237], off offset:256
	s_waitcnt vmcnt(7)
	v_mad_i64_i32 v[248:249], vcc, s17, v148, 0
	v_lshl_add_u64 v[248:249], v[248:249], 1, v[156:157]
	v_lshlrev_b32_e32 v168, 16, v194
	v_and_b32_e32 v169, 0xffff0000, v194
	v_lshlrev_b32_e32 v170, 16, v198
	v_and_b32_e32 v171, 0xffff0000, v198
	v_lshlrev_b32_e32 v172, 16, v195
	v_and_b32_e32 v173, 0xffff0000, v195
	v_lshlrev_b32_e32 v174, 16, v199
	v_and_b32_e32 v175, 0xffff0000, v199
	v_pk_fma_f32 v[168:169], v[178:179], v[170:171], v[168:169]
	v_pk_fma_f32 v[172:173], v[180:181], v[174:175], v[172:173]
	v_pk_fma_f32 v[12:13], v[186:187], v[12:13], v[168:169]
	v_pk_fma_f32 v[14:15], v[188:189], v[14:15], v[172:173]
	v_lshlrev_b32_e32 v168, 16, v196
	v_and_b32_e32 v169, 0xffff0000, v196
	v_lshlrev_b32_e32 v170, 16, v200
	v_and_b32_e32 v171, 0xffff0000, v200
	v_lshlrev_b32_e32 v172, 16, v197
	v_and_b32_e32 v173, 0xffff0000, v197
	v_lshlrev_b32_e32 v174, 16, v201
	v_and_b32_e32 v175, 0xffff0000, v201
	v_pk_fma_f32 v[168:169], v[182:183], v[170:171], v[168:169]
	v_pk_fma_f32 v[172:173], v[184:185], v[174:175], v[172:173]
	v_pk_fma_f32 v[8:9], v[190:191], v[8:9], v[168:169]
	v_pk_fma_f32 v[10:11], v[192:193], v[10:11], v[172:173]
	s_nop 0
	v_cvt_pk_bf16_f32 v234, v12, v13
	v_cvt_pk_bf16_f32 v235, v14, v15
	v_cvt_pk_bf16_f32 v236, v8, v9
	v_cvt_pk_bf16_f32 v237, v10, v11
	global_store_dwordx4 v[248:249], v[234:237], off offset:256
	s_waitcnt vmcnt(5)
	v_mad_i64_i32 v[248:249], vcc, s17, v150, 0
	v_lshl_add_u64 v[248:249], v[248:249], 1, v[156:157]
	v_lshlrev_b32_e32 v168, 16, v202
	v_and_b32_e32 v169, 0xffff0000, v202
	v_lshlrev_b32_e32 v170, 16, v206
	v_and_b32_e32 v171, 0xffff0000, v206
	v_lshlrev_b32_e32 v172, 16, v203
	v_and_b32_e32 v173, 0xffff0000, v203
	v_lshlrev_b32_e32 v174, 16, v207
	v_and_b32_e32 v175, 0xffff0000, v207
	v_pk_fma_f32 v[168:169], v[178:179], v[170:171], v[168:169]
	v_pk_fma_f32 v[172:173], v[180:181], v[174:175], v[172:173]
	v_pk_fma_f32 v[4:5], v[186:187], v[4:5], v[168:169]
	v_pk_fma_f32 v[6:7], v[188:189], v[6:7], v[172:173]
	v_lshlrev_b32_e32 v168, 16, v204
	v_and_b32_e32 v169, 0xffff0000, v204
	v_lshlrev_b32_e32 v170, 16, v208
	v_and_b32_e32 v171, 0xffff0000, v208
	v_lshlrev_b32_e32 v172, 16, v205
	v_and_b32_e32 v173, 0xffff0000, v205
	v_lshlrev_b32_e32 v174, 16, v209
	v_and_b32_e32 v175, 0xffff0000, v209
	v_pk_fma_f32 v[168:169], v[182:183], v[170:171], v[168:169]
	v_pk_fma_f32 v[172:173], v[184:185], v[174:175], v[172:173]
	v_pk_fma_f32 v[0:1], v[190:191], v[0:1], v[168:169]
	v_pk_fma_f32 v[2:3], v[192:193], v[2:3], v[172:173]
	s_nop 0
	v_cvt_pk_bf16_f32 v234, v4, v5
	v_cvt_pk_bf16_f32 v235, v6, v7
	v_cvt_pk_bf16_f32 v236, v0, v1
	v_cvt_pk_bf16_f32 v237, v2, v3
	global_store_dwordx4 v[248:249], v[234:237], off offset:256
	s_and_b64 vcc, exec, s[40:41]
	s_mov_b32 s38, s75
	s_mov_b32 s34, s73
	s_mov_b32 s30, s74
	s_mov_b64 s[48:49], s[36:37]
	s_mov_b64 s[46:47], s[42:43]
	s_cbranch_vccnz .LBB0_1346
	s_branch .LBB0_1327
